# dead m0 writes also removed from the P4-Cq, P6 and P3 load segments
# baseline (speedup 1.0000x reference)
; #define PG8_STAGE(bufoff, gbase, voff) do { _Pragma("unroll") for (int _i = 0; _i < 2; ++_i) \
;         __builtin_amdgcn_global_load_lds((const unsigned*)((const char*)(gbase) + (voff)[_i]), (PG8_LAS unsigned*)(lds + (bufoff) + ldsw + _i * 8192), 16, 0, 0); } while (0)
; #define PG8_LDA(dst, b, h) do { _Pragma("unroll") for (int m = 0; m < 4; ++m) _Pragma("unroll") for (int k = 0; k < 2; ++k) dst[m][k] = *(const PG8_LAS bf16x8*)(lds + PG8_SA(b, h) + aoff + m * 2048 + k * 1024); } while (0)
; #define PG8_LDB(dst, b, h) do { _Pragma("unroll") for (int n = 0; n < 2; ++n) _Pragma("unroll") for (int k = 0; k < 2; ++k) dst[n][k] = *(const PG8_LAS bf16x8*)(lds + PG8_SB(b, h) + boff + n * 2048 + k * 1024); } while (0)
; #define PG8_MMA(ai, bj, At, Bt) do { __builtin_amdgcn_s_setprio(1); _Pragma("unroll") for (int m = 0; m < 4; ++m) _Pragma("unroll") for (int n = 0; n < 2; ++n) _Pragma("unroll") for (int k = 0; k < 2; ++k) \
;         acc[ai][bj][m][n] = __builtin_amdgcn_mfma_f32_16x16x32_bf16(Bt[n][k], At[m][k], acc[ai][bj][m][n], 0, 0, 0); __builtin_amdgcn_s_setprio(0); } while (0)
; #define PG8_WAIT_V(n) asm volatile("s_waitcnt vmcnt(" #n ")" ::: "memory")
; #define PG8_WAIT_L(n) asm volatile("s_waitcnt lgkmcnt(" #n ")" ::: "memory")
; #define PG8_BAR __builtin_amdgcn_s_barrier()
; template <class Epi, class Sched, bool ALIGN_EPI = false, bool SP2 = false>
; __device__ __forceinline__ void gemm_phase(PG8_LAS unsigned char* lds, const Gemm g, const Sched& S, const Epi& E) {
;     ...
;             const char* a1 = cA + (size_t)(t + 1) * kstep;
;             const char* a2 = last ? nA : cA + (size_t)(t + 2) * kstep; const char* b2 = last ? nB : cB + (size_t)(t + 2) * kstep;
;             const char* a3 = a2 + kstep; const char* b3 = b2 + kstep;
;             if (last && has_next) S.a_ready(nxt);
;             if constexpr (SP2) {
;             PG8_LDB(B0, 0, 0); PG8_LDB(B1, 0, 1); PG8_SCHED; PG8_LDA(At, 0, 0); PG8_STAGE(PG8_SA(1, 1), a1 + hstepA, voffA);
;             PG8_WAIT_V(8); PG8_WAIT_L(0); PG8_BAR; PG8_MMA(0, 0, At, B0); PG8_MMA(0, 1, At, B1); PG8_BAR; PG8_SCHED;
;             PG8_LDA(At, 0, 1); PG8_STAGE(PG8_SB(0, 0), b2, voffB); PG8_STAGE(PG8_SB(0, 1), b2 + hstepB, voffB); PG8_STAGE(PG8_SA(0, 0), a2, voffA);
;             PG8_WAIT_V(8); PG8_WAIT_L(0); PG8_BAR; PG8_MMA(1, 0, At, B0); PG8_MMA(1, 1, At, B1); PG8_BAR; PG8_SCHED;
.LBB0_1217:
	v_add_u32_e32 v1, s57, v154
	ds_read_b128 v[158:161], v1
	ds_read_b128 v[162:165], v1 offset:1024
	ds_read_b128 v[166:169], v1 offset:2048
	ds_read_b128 v[170:173], v1 offset:3072
	v_add_u32_e32 v1, s58, v154
	s_add_u32 s42, s78, s18
	ds_read_b128 v[174:177], v1
	ds_read_b128 v[178:181], v1 offset:1024
	ds_read_b128 v[182:185], v1 offset:2048
	ds_read_b128 v[186:189], v1 offset:3072
	s_addc_u32 s43, s79, s19
	s_add_u32 s42, s42, 0x100
	s_addc_u32 s43, s43, 0
	s_add_u32 s69, s66, s18
	s_addc_u32 s70, s67, s19
	s_cmpk_eq_i32 s18, 0xf00
	s_cselect_b32 s43, s62, s43
	s_cselect_b32 s42, s63, s42
	s_cselect_b32 vcc_hi, s51, s70
	s_cselect_b32 vcc_lo, s65, s69
	v_lshl_add_u64 v[2:3], v[148:149], 0, s[18:19]
	ds_read_b128 v[190:193], v156
	ds_read_b128 v[194:197], v156 offset:1024
	ds_read_b128 v[198:201], v156 offset:2048
	ds_read_b128 v[202:205], v156 offset:3072
	ds_read_b128 v[206:209], v156 offset:4096
	ds_read_b128 v[210:213], v156 offset:5120
	ds_read_b128 v[214:217], v156 offset:6144
	ds_read_b128 v[218:221], v156 offset:7168
	s_add_u32 s98, s78, s18
	s_addc_u32 s99, s79, s19
	s_add_u32 s98, s98, 0x80
	s_addc_u32 s99, s99, 0
	s_mov_b32 m0, s47
	s_nop 0
	global_load_lds_dwordx4 v132, s[98:99]
	s_mov_b32 m0, s56
	s_nop 0
	global_load_lds_dwordx4 v136, s[98:99]
	s_add_i32 m0, s5, 0xc000
	s_nop 0
	global_load_lds_dwordx4 v[2:3], off
	v_lshl_add_u64 v[2:3], v[150:151], 0, s[18:19]
	s_add_i32 m0, s5, 0xe000
	s_nop 0
	global_load_lds_dwordx4 v[2:3], off
	s_waitcnt vmcnt(8)
	s_waitcnt lgkmcnt(0)
	s_barrier
	s_setprio 1
	s_waitcnt lgkmcnt(0)
	v_mfma_f32_16x16x32_bf16 v[128:131], v[158:161], v[190:193], v[128:131]
	v_mfma_f32_16x16x32_bf16 v[124:127], v[166:169], v[190:193], v[124:127]
	v_mfma_f32_16x16x32_bf16 v[112:115], v[158:161], v[198:201], v[112:115]
	v_mfma_f32_16x16x32_bf16 v[108:111], v[166:169], v[198:201], v[108:111]
	v_mfma_f32_16x16x32_bf16 v[96:99], v[158:161], v[206:209], v[96:99]
	v_mfma_f32_16x16x32_bf16 v[92:95], v[166:169], v[206:209], v[92:95]
	v_mfma_f32_16x16x32_bf16 v[80:83], v[158:161], v[214:217], v[80:83]
	v_mfma_f32_16x16x32_bf16 v[76:79], v[166:169], v[214:217], v[76:79]
	v_mfma_f32_16x16x32_bf16 v[128:131], v[162:165], v[194:197], v[128:131]
	v_mfma_f32_16x16x32_bf16 v[124:127], v[170:173], v[194:197], v[124:127]
	v_mfma_f32_16x16x32_bf16 v[112:115], v[162:165], v[202:205], v[112:115]
	v_mfma_f32_16x16x32_bf16 v[108:111], v[170:173], v[202:205], v[108:111]
	v_mfma_f32_16x16x32_bf16 v[96:99], v[162:165], v[210:213], v[96:99]
	v_mfma_f32_16x16x32_bf16 v[92:95], v[170:173], v[210:213], v[92:95]
	v_mfma_f32_16x16x32_bf16 v[80:83], v[162:165], v[218:221], v[80:83]
	v_mfma_f32_16x16x32_bf16 v[76:79], v[170:173], v[218:221], v[76:79]
	s_setprio 0
	s_setprio 1
	v_mfma_f32_16x16x32_bf16 v[120:123], v[174:177], v[190:193], v[120:123]
	v_mfma_f32_16x16x32_bf16 v[116:119], v[182:185], v[190:193], v[116:119]
	v_mfma_f32_16x16x32_bf16 v[104:107], v[174:177], v[198:201], v[104:107]
	v_mfma_f32_16x16x32_bf16 v[100:103], v[182:185], v[198:201], v[100:103]
	v_mfma_f32_16x16x32_bf16 v[88:91], v[174:177], v[206:209], v[88:91]
	v_mfma_f32_16x16x32_bf16 v[84:87], v[182:185], v[206:209], v[84:87]
	v_mfma_f32_16x16x32_bf16 v[72:75], v[174:177], v[214:217], v[72:75]
	v_mfma_f32_16x16x32_bf16 v[68:71], v[182:185], v[214:217], v[68:71]
	v_mfma_f32_16x16x32_bf16 v[120:123], v[178:181], v[194:197], v[120:123]
	v_mfma_f32_16x16x32_bf16 v[116:119], v[186:189], v[194:197], v[116:119]
	v_mfma_f32_16x16x32_bf16 v[104:107], v[178:181], v[202:205], v[104:107]
	v_mfma_f32_16x16x32_bf16 v[100:103], v[186:189], v[202:205], v[100:103]
	v_mfma_f32_16x16x32_bf16 v[88:91], v[178:181], v[210:213], v[88:91]
	v_mfma_f32_16x16x32_bf16 v[84:87], v[186:189], v[210:213], v[84:87]
	v_mfma_f32_16x16x32_bf16 v[72:75], v[178:181], v[218:221], v[72:75]
	v_mfma_f32_16x16x32_bf16 v[68:71], v[186:189], v[218:221], v[68:71]
	s_setprio 0
	s_barrier
	s_add_i32 s69, s57, s4
	s_mov_b32 m0, s69
	ds_read_b128 v[190:193], v156 offset:16384
	ds_read_b128 v[194:197], v156 offset:17408
	ds_read_b128 v[198:201], v156 offset:18432
	ds_read_b128 v[202:205], v156 offset:19456
	ds_read_b128 v[206:209], v156 offset:20480
	ds_read_b128 v[210:213], v156 offset:21504
	ds_read_b128 v[214:217], v156 offset:22528
	ds_read_b128 v[218:221], v156 offset:23552
	global_load_lds_dwordx4 v134, vcc
	s_add_i32 m0, s69, 0x2000
	s_add_u32 s70, vcc_lo, 0x80000
	s_addc_u32 s71, vcc_hi, 0
	s_add_i32 s69, s58, s4
	global_load_lds_dwordx4 v138, vcc
	s_mov_b32 m0, s69
	s_nop 0
	global_load_lds_dwordx4 v134, s[70:71]
	s_add_i32 m0, s69, 0x2000
	s_nop 0
	global_load_lds_dwordx4 v138, s[70:71]
	s_waitcnt vmcnt(6)
	s_waitcnt lgkmcnt(0)
	s_barrier
; #define PG8_STAGE(bufoff, gbase, voff) do { _Pragma("unroll") for (int _i = 0; _i < 2; ++_i) \
;         __builtin_amdgcn_global_load_lds((const unsigned*)((const char*)(gbase) + (voff)[_i]), (PG8_LAS unsigned*)(lds + (bufoff) + ldsw + _i * 8192), 16, 0, 0); } while (0)
; #define PG8_LDA(dst, b, h) do { _Pragma("unroll") for (int m = 0; m < 4; ++m) _Pragma("unroll") for (int k = 0; k < 2; ++k) dst[m][k] = *(const PG8_LAS bf16x8*)(lds + PG8_SA(b, h) + aoff + m * 2048 + k * 1024); } while (0)
; #define PG8_LDB(dst, b, h) do { _Pragma("unroll") for (int n = 0; n < 2; ++n) _Pragma("unroll") for (int k = 0; k < 2; ++k) dst[n][k] = *(const PG8_LAS bf16x8*)(lds + PG8_SB(b, h) + boff + n * 2048 + k * 1024); } while (0)
; #define PG8_MMA(ai, bj, At, Bt) do { __builtin_amdgcn_s_setprio(1); _Pragma("unroll") for (int m = 0; m < 4; ++m) _Pragma("unroll") for (int n = 0; n < 2; ++n) _Pragma("unroll") for (int k = 0; k < 2; ++k) \
;         acc[ai][bj][m][n] = __builtin_amdgcn_mfma_f32_16x16x32_bf16(Bt[n][k], At[m][k], acc[ai][bj][m][n], 0, 0, 0); __builtin_amdgcn_s_setprio(0); } while (0)
; #define PG8_WAIT_V(n) asm volatile("s_waitcnt vmcnt(" #n ")" ::: "memory")
; #define PG8_WAIT_L(n) asm volatile("s_waitcnt lgkmcnt(" #n ")" ::: "memory")
; #define PG8_BAR __builtin_amdgcn_s_barrier()
; #define PG8_SCHED __builtin_amdgcn_sched_barrier(0)
; template <class Epi, class Sched, bool ALIGN_EPI = false, bool SP2 = false>
; __device__ __forceinline__ void gemm_phase(PG8_LAS unsigned char* lds, const Gemm g, const Sched& S, const Epi& E) {
;     ...
;             PG8_WAIT_V(8); PG8_WAIT_L(0); PG8_BAR; PG8_MMA(0, 0, At, B0); PG8_MMA(0, 1, At, B1); PG8_BAR; PG8_SCHED;
;             PG8_LDA(At, 0, 1); PG8_STAGE(PG8_SB(0, 0), b2, voffB); PG8_STAGE(PG8_SB(0, 1), b2 + hstepB, voffB); PG8_STAGE(PG8_SA(0, 0), a2, voffA);
;             PG8_WAIT_V(8); PG8_WAIT_L(0); PG8_BAR; PG8_MMA(1, 0, At, B0); PG8_MMA(1, 1, At, B1); PG8_BAR; PG8_SCHED;
;             PG8_LDB(B0, 1, 0); PG8_LDB(B1, 1, 1); PG8_SCHED; PG8_LDA(At, 1, 0); PG8_STAGE(PG8_SA(0, 1), a2 + hstepA, voffA);
;             PG8_WAIT_V(8); PG8_WAIT_L(0); PG8_BAR; PG8_MMA(0, 0, At, B0); PG8_MMA(0, 1, At, B1); PG8_BAR; PG8_SCHED;
;             PG8_LDA(At, 1, 1); PG8_STAGE(PG8_SB(1, 0), b3, voffB); PG8_STAGE(PG8_SB(1, 1), b3 + hstepB, voffB); PG8_STAGE(PG8_SA(1, 0), a3, voffA);
	s_setprio 1
	s_waitcnt lgkmcnt(0)
	v_mfma_f32_16x16x32_bf16 v[64:67], v[158:161], v[190:193], v[64:67]
	v_mfma_f32_16x16x32_bf16 v[60:63], v[166:169], v[190:193], v[60:63]
	v_mfma_f32_16x16x32_bf16 v[48:51], v[158:161], v[198:201], v[48:51]
	v_mfma_f32_16x16x32_bf16 v[44:47], v[166:169], v[198:201], v[44:47]
	v_mfma_f32_16x16x32_bf16 v[32:35], v[158:161], v[206:209], v[32:35]
	v_mfma_f32_16x16x32_bf16 v[28:31], v[166:169], v[206:209], v[28:31]
	v_mfma_f32_16x16x32_bf16 v[16:19], v[158:161], v[214:217], v[16:19]
	v_mfma_f32_16x16x32_bf16 v[12:15], v[166:169], v[214:217], v[12:15]
	v_mfma_f32_16x16x32_bf16 v[64:67], v[162:165], v[194:197], v[64:67]
	v_mfma_f32_16x16x32_bf16 v[60:63], v[170:173], v[194:197], v[60:63]
	v_mfma_f32_16x16x32_bf16 v[48:51], v[162:165], v[202:205], v[48:51]
	v_mfma_f32_16x16x32_bf16 v[44:47], v[170:173], v[202:205], v[44:47]
	v_mfma_f32_16x16x32_bf16 v[32:35], v[162:165], v[210:213], v[32:35]
	v_mfma_f32_16x16x32_bf16 v[28:31], v[170:173], v[210:213], v[28:31]
	v_mfma_f32_16x16x32_bf16 v[16:19], v[162:165], v[218:221], v[16:19]
	v_mfma_f32_16x16x32_bf16 v[12:15], v[170:173], v[218:221], v[12:15]
	s_setprio 0
	s_setprio 1
	v_mfma_f32_16x16x32_bf16 v[56:59], v[174:177], v[190:193], v[56:59]
	v_mfma_f32_16x16x32_bf16 v[52:55], v[182:185], v[190:193], v[52:55]
	v_mfma_f32_16x16x32_bf16 v[40:43], v[174:177], v[198:201], v[40:43]
	v_mfma_f32_16x16x32_bf16 v[36:39], v[182:185], v[198:201], v[36:39]
	v_mfma_f32_16x16x32_bf16 v[24:27], v[174:177], v[206:209], v[24:27]
	v_mfma_f32_16x16x32_bf16 v[20:23], v[182:185], v[206:209], v[20:23]
	v_mfma_f32_16x16x32_bf16 v[8:11], v[174:177], v[214:217], v[8:11]
	v_mfma_f32_16x16x32_bf16 v[2:5], v[182:185], v[214:217], v[4:7]
	v_mfma_f32_16x16x32_bf16 v[56:59], v[178:181], v[194:197], v[56:59]
	v_mfma_f32_16x16x32_bf16 v[52:55], v[186:189], v[194:197], v[52:55]
	v_mfma_f32_16x16x32_bf16 v[40:43], v[178:181], v[202:205], v[40:43]
	v_mfma_f32_16x16x32_bf16 v[36:39], v[186:189], v[202:205], v[36:39]
	v_mfma_f32_16x16x32_bf16 v[24:27], v[178:181], v[210:213], v[24:27]
	v_mfma_f32_16x16x32_bf16 v[20:23], v[186:189], v[210:213], v[20:23]
	v_mfma_f32_16x16x32_bf16 v[8:11], v[178:181], v[218:221], v[8:11]
	v_mfma_f32_16x16x32_bf16 v[2:5], v[186:189], v[218:221], v[2:5]
	s_setprio 0
	s_barrier
	s_add_i32 s69, 0, 0x18000
	v_add_u32_e32 v1, s69, v154
	s_add_i32 s70, 0, 0x1c000
	ds_read_b128 v[158:161], v1
	ds_read_b128 v[162:165], v1 offset:1024
	ds_read_b128 v[166:169], v1 offset:2048
	ds_read_b128 v[170:173], v1 offset:3072
	v_add_u32_e32 v1, s70, v154
	ds_read_b128 v[174:177], v1
	ds_read_b128 v[178:181], v1 offset:1024
	ds_read_b128 v[182:185], v1 offset:2048
	ds_read_b128 v[186:189], v1 offset:3072
	s_mov_b64 s[100:101], s[42:43]
	s_add_u32 s42, s42, 0x80000
	s_addc_u32 s43, s43, 0
	ds_read_b128 v[190:193], v156 offset:32768
	ds_read_b128 v[194:197], v156 offset:33792
	ds_read_b128 v[198:201], v156 offset:34816
	ds_read_b128 v[202:205], v156 offset:35840
	ds_read_b128 v[206:209], v156 offset:36864
	ds_read_b128 v[210:213], v156 offset:37888
	ds_read_b128 v[214:217], v156 offset:38912
	ds_read_b128 v[218:221], v156 offset:39936
	s_mov_b32 m0, s5
	s_nop 0
	global_load_lds_dwordx4 v132, s[100:101]
	s_mov_b32 m0, s6
	s_nop 0
	global_load_lds_dwordx4 v136, s[100:101]
	s_mov_b32 m0, s7
	s_nop 0
	global_load_lds_dwordx4 v132, s[42:43]
	s_mov_b32 m0, s33
	s_nop 0
	global_load_lds_dwordx4 v136, s[42:43]
	s_waitcnt vmcnt(8)
	s_waitcnt lgkmcnt(0)
	s_barrier
; #define PG8_STAGE(bufoff, gbase, voff) do { _Pragma("unroll") for (int _i = 0; _i < 2; ++_i) \
;         __builtin_amdgcn_global_load_lds((const unsigned*)((const char*)(gbase) + (voff)[_i]), (PG8_LAS unsigned*)(lds + (bufoff) + ldsw + _i * 8192), 16, 0, 0); } while (0)
; #define PG8_LDA(dst, b, h) do { _Pragma("unroll") for (int m = 0; m < 4; ++m) _Pragma("unroll") for (int k = 0; k < 2; ++k) dst[m][k] = *(const PG8_LAS bf16x8*)(lds + PG8_SA(b, h) + aoff + m * 2048 + k * 1024); } while (0)
; #define PG8_MMA(ai, bj, At, Bt) do { __builtin_amdgcn_s_setprio(1); _Pragma("unroll") for (int m = 0; m < 4; ++m) _Pragma("unroll") for (int n = 0; n < 2; ++n) _Pragma("unroll") for (int k = 0; k < 2; ++k) \
;         acc[ai][bj][m][n] = __builtin_amdgcn_mfma_f32_16x16x32_bf16(Bt[n][k], At[m][k], acc[ai][bj][m][n], 0, 0, 0); __builtin_amdgcn_s_setprio(0); } while (0)
; #define PG8_WAIT_V(n) asm volatile("s_waitcnt vmcnt(" #n ")" ::: "memory")
; #define PG8_WAIT_L(n) asm volatile("s_waitcnt lgkmcnt(" #n ")" ::: "memory")
; #define PG8_BAR __builtin_amdgcn_s_barrier()
; #define PG8_SCHED __builtin_amdgcn_sched_barrier(0)
; template <class Epi, class Sched, bool ALIGN_EPI = false, bool SP2 = false>
; __device__ __forceinline__ void gemm_phase(PG8_LAS unsigned char* lds, const Gemm g, const Sched& S, const Epi& E) {
;     ...
;         for (int t = 0; t < nt; t += 2) {
;     ...
;             PG8_WAIT_V(8); PG8_WAIT_L(0); PG8_BAR; PG8_MMA(0, 0, At, B0); PG8_MMA(0, 1, At, B1); PG8_BAR; PG8_SCHED;
;             PG8_LDA(At, 1, 1); PG8_STAGE(PG8_SB(1, 0), b3, voffB); PG8_STAGE(PG8_SB(1, 1), b3 + hstepB, voffB); PG8_STAGE(PG8_SA(1, 0), a3, voffA);
;             PG8_WAIT_V(8); PG8_WAIT_L(0); PG8_BAR; PG8_MMA(1, 0, At, B0); PG8_MMA(1, 1, At, B1); PG8_BAR; PG8_SCHED;
	s_setprio 1
	s_waitcnt lgkmcnt(0)
	v_mfma_f32_16x16x32_bf16 v[128:131], v[158:161], v[190:193], v[128:131]
	v_mfma_f32_16x16x32_bf16 v[124:127], v[166:169], v[190:193], v[124:127]
	v_mfma_f32_16x16x32_bf16 v[112:115], v[158:161], v[198:201], v[112:115]
	v_mfma_f32_16x16x32_bf16 v[108:111], v[166:169], v[198:201], v[108:111]
	v_mfma_f32_16x16x32_bf16 v[96:99], v[158:161], v[206:209], v[96:99]
	v_mfma_f32_16x16x32_bf16 v[92:95], v[166:169], v[206:209], v[92:95]
	v_mfma_f32_16x16x32_bf16 v[80:83], v[158:161], v[214:217], v[80:83]
	v_mfma_f32_16x16x32_bf16 v[76:79], v[166:169], v[214:217], v[76:79]
	v_mfma_f32_16x16x32_bf16 v[128:131], v[162:165], v[194:197], v[128:131]
	v_mfma_f32_16x16x32_bf16 v[124:127], v[170:173], v[194:197], v[124:127]
	v_mfma_f32_16x16x32_bf16 v[112:115], v[162:165], v[202:205], v[112:115]
	v_mfma_f32_16x16x32_bf16 v[108:111], v[170:173], v[202:205], v[108:111]
	v_mfma_f32_16x16x32_bf16 v[96:99], v[162:165], v[210:213], v[96:99]
	v_mfma_f32_16x16x32_bf16 v[92:95], v[170:173], v[210:213], v[92:95]
	v_mfma_f32_16x16x32_bf16 v[80:83], v[162:165], v[218:221], v[80:83]
	v_mfma_f32_16x16x32_bf16 v[76:79], v[170:173], v[218:221], v[76:79]
	s_setprio 0
	s_setprio 1
	v_mfma_f32_16x16x32_bf16 v[120:123], v[174:177], v[190:193], v[120:123]
	v_mfma_f32_16x16x32_bf16 v[116:119], v[182:185], v[190:193], v[116:119]
	v_mfma_f32_16x16x32_bf16 v[104:107], v[174:177], v[198:201], v[104:107]
	v_mfma_f32_16x16x32_bf16 v[100:103], v[182:185], v[198:201], v[100:103]
	v_mfma_f32_16x16x32_bf16 v[88:91], v[174:177], v[206:209], v[88:91]
	v_mfma_f32_16x16x32_bf16 v[84:87], v[182:185], v[206:209], v[84:87]
	v_mfma_f32_16x16x32_bf16 v[72:75], v[174:177], v[214:217], v[72:75]
	v_mfma_f32_16x16x32_bf16 v[68:71], v[182:185], v[214:217], v[68:71]
	v_mfma_f32_16x16x32_bf16 v[120:123], v[178:181], v[194:197], v[120:123]
	v_mfma_f32_16x16x32_bf16 v[116:119], v[186:189], v[194:197], v[116:119]
	v_mfma_f32_16x16x32_bf16 v[104:107], v[178:181], v[202:205], v[104:107]
	v_mfma_f32_16x16x32_bf16 v[100:103], v[186:189], v[202:205], v[100:103]
	v_mfma_f32_16x16x32_bf16 v[88:91], v[178:181], v[210:213], v[88:91]
	v_mfma_f32_16x16x32_bf16 v[84:87], v[186:189], v[210:213], v[84:87]
	v_mfma_f32_16x16x32_bf16 v[72:75], v[178:181], v[218:221], v[72:75]
	v_mfma_f32_16x16x32_bf16 v[68:71], v[186:189], v[218:221], v[68:71]
	s_setprio 0
	s_barrier
	s_add_i32 s42, s69, s4
	s_add_u32 s98, vcc_lo, 0x80
	s_addc_u32 s99, vcc_hi, 0
	s_mov_b32 m0, s42
	ds_read_b128 v[190:193], v156 offset:49152
	ds_read_b128 v[194:197], v156 offset:50176
	ds_read_b128 v[198:201], v156 offset:51200
	ds_read_b128 v[202:205], v156 offset:52224
	ds_read_b128 v[206:209], v156 offset:53248
	ds_read_b128 v[210:213], v156 offset:54272
	ds_read_b128 v[214:217], v156 offset:55296
	ds_read_b128 v[218:221], v156 offset:56320
	global_load_lds_dwordx4 v134, s[98:99]
	s_add_i32 m0, s42, 0x2000
	s_add_u32 s42, vcc_lo, 0x80080
	s_addc_u32 s43, vcc_hi, 0
	s_add_i32 s69, s70, s4
	global_load_lds_dwordx4 v138, s[98:99]
	s_mov_b32 m0, s69
	s_nop 0
	global_load_lds_dwordx4 v134, s[42:43]
	s_add_i32 m0, s69, 0x2000
	s_nop 0
	global_load_lds_dwordx4 v138, s[42:43]
	s_waitcnt vmcnt(6)
	s_waitcnt lgkmcnt(0)
	s_barrier
	s_setprio 1
	s_waitcnt lgkmcnt(0)
	v_mfma_f32_16x16x32_bf16 v[64:67], v[158:161], v[190:193], v[64:67]
	v_mfma_f32_16x16x32_bf16 v[60:63], v[166:169], v[190:193], v[60:63]
	v_mfma_f32_16x16x32_bf16 v[48:51], v[158:161], v[198:201], v[48:51]
	v_mfma_f32_16x16x32_bf16 v[44:47], v[166:169], v[198:201], v[44:47]
	v_mfma_f32_16x16x32_bf16 v[32:35], v[158:161], v[206:209], v[32:35]
	v_mfma_f32_16x16x32_bf16 v[28:31], v[166:169], v[206:209], v[28:31]
	v_mfma_f32_16x16x32_bf16 v[16:19], v[158:161], v[214:217], v[16:19]
	v_mfma_f32_16x16x32_bf16 v[12:15], v[166:169], v[214:217], v[12:15]
	v_mfma_f32_16x16x32_bf16 v[64:67], v[162:165], v[194:197], v[64:67]
	v_mfma_f32_16x16x32_bf16 v[60:63], v[170:173], v[194:197], v[60:63]
	v_mfma_f32_16x16x32_bf16 v[48:51], v[162:165], v[202:205], v[48:51]
	v_mfma_f32_16x16x32_bf16 v[44:47], v[170:173], v[202:205], v[44:47]
	v_mfma_f32_16x16x32_bf16 v[32:35], v[162:165], v[210:213], v[32:35]
	v_mfma_f32_16x16x32_bf16 v[28:31], v[170:173], v[210:213], v[28:31]
	v_mfma_f32_16x16x32_bf16 v[16:19], v[162:165], v[218:221], v[16:19]
	v_mfma_f32_16x16x32_bf16 v[12:15], v[170:173], v[218:221], v[12:15]
	s_setprio 0
	s_setprio 1
	v_mfma_f32_16x16x32_bf16 v[56:59], v[174:177], v[190:193], v[56:59]
	v_mfma_f32_16x16x32_bf16 v[52:55], v[182:185], v[190:193], v[52:55]
	v_mfma_f32_16x16x32_bf16 v[40:43], v[174:177], v[198:201], v[40:43]
	v_mfma_f32_16x16x32_bf16 v[36:39], v[182:185], v[198:201], v[36:39]
	v_mfma_f32_16x16x32_bf16 v[24:27], v[174:177], v[206:209], v[24:27]
	v_mfma_f32_16x16x32_bf16 v[20:23], v[182:185], v[206:209], v[20:23]
	v_mfma_f32_16x16x32_bf16 v[6:9], v[174:177], v[214:217], v[8:11]
	v_mfma_f32_16x16x32_bf16 v[2:5], v[182:185], v[214:217], v[2:5]
	v_mfma_f32_16x16x32_bf16 v[56:59], v[178:181], v[194:197], v[56:59]
	v_mfma_f32_16x16x32_bf16 v[52:55], v[186:189], v[194:197], v[52:55]
	v_mfma_f32_16x16x32_bf16 v[40:43], v[178:181], v[202:205], v[40:43]
	v_mfma_f32_16x16x32_bf16 v[36:39], v[186:189], v[202:205], v[36:39]
	v_mfma_f32_16x16x32_bf16 v[24:27], v[178:181], v[210:213], v[24:27]
	v_mfma_f32_16x16x32_bf16 v[20:23], v[186:189], v[210:213], v[20:23]
	v_mfma_f32_16x16x32_bf16 v[8:11], v[178:181], v[218:221], v[6:9]
	v_mfma_f32_16x16x32_bf16 v[4:7], v[186:189], v[218:221], v[2:5]
	s_setprio 0
	s_barrier
	s_add_i32 s68, s68, 2
	s_add_u32 s18, s18, 0x100
	s_addc_u32 s19, s19, 0
	s_cmp_gt_u32 s68, 29
	s_cbranch_scc1 .LBB0_1220

; #define PG8_STAGE(bufoff, gbase, voff) do { _Pragma("unroll") for (int _i = 0; _i < 2; ++_i) \
;         __builtin_amdgcn_global_load_lds((const unsigned*)((const char*)(gbase) + (voff)[_i]), (PG8_LAS unsigned*)(lds + (bufoff) + ldsw + _i * 8192), 16, 0, 0); } while (0)
; #define PG8_LDA(dst, b, h) do { _Pragma("unroll") for (int m = 0; m < 4; ++m) _Pragma("unroll") for (int k = 0; k < 2; ++k) dst[m][k] = *(const PG8_LAS bf16x8*)(lds + PG8_SA(b, h) + aoff + m * 2048 + k * 1024); } while (0)
; #define PG8_LDB(dst, b, h) do { _Pragma("unroll") for (int n = 0; n < 2; ++n) _Pragma("unroll") for (int k = 0; k < 2; ++k) dst[n][k] = *(const PG8_LAS bf16x8*)(lds + PG8_SB(b, h) + boff + n * 2048 + k * 1024); } while (0)
; #define PG8_MMA(ai, bj, At, Bt) do { __builtin_amdgcn_s_setprio(1); _Pragma("unroll") for (int m = 0; m < 4; ++m) _Pragma("unroll") for (int n = 0; n < 2; ++n) _Pragma("unroll") for (int k = 0; k < 2; ++k) \
;         acc[ai][bj][m][n] = __builtin_amdgcn_mfma_f32_16x16x32_bf16(Bt[n][k], At[m][k], acc[ai][bj][m][n], 0, 0, 0); __builtin_amdgcn_s_setprio(0); } while (0)
; #define PG8_WAIT_V(n) asm volatile("s_waitcnt vmcnt(" #n ")" ::: "memory")
; #define PG8_WAIT_L(n) asm volatile("s_waitcnt lgkmcnt(" #n ")" ::: "memory")
; #define PG8_BAR __builtin_amdgcn_s_barrier()
; template <class Epi, class Sched, bool ALIGN_EPI = false, bool SP2 = false>
; __device__ __forceinline__ void gemm_phase(PG8_LAS unsigned char* lds, const Gemm g, const Sched& S, const Epi& E) {
;     ...
;             const char* a1 = cA + (size_t)(t + 1) * kstep;
;             const char* a2 = last ? nA : cA + (size_t)(t + 2) * kstep; const char* b2 = last ? nB : cB + (size_t)(t + 2) * kstep;
;             const char* a3 = a2 + kstep; const char* b3 = b2 + kstep;
;             if (last && has_next) S.a_ready(nxt);
;             if constexpr (SP2) {
;             PG8_LDB(B0, 0, 0); PG8_LDB(B1, 0, 1); PG8_SCHED; PG8_LDA(At, 0, 0); PG8_STAGE(PG8_SA(1, 1), a1 + hstepA, voffA);
;             PG8_WAIT_V(8); PG8_WAIT_L(0); PG8_BAR; PG8_MMA(0, 0, At, B0); PG8_MMA(0, 1, At, B1); PG8_BAR; PG8_SCHED;
;             PG8_LDA(At, 0, 1); PG8_STAGE(PG8_SB(0, 0), b2, voffB); PG8_STAGE(PG8_SB(0, 1), b2 + hstepB, voffB); PG8_STAGE(PG8_SA(0, 0), a2, voffA);
;             PG8_WAIT_V(8); PG8_WAIT_L(0); PG8_BAR; PG8_MMA(1, 0, At, B0); PG8_MMA(1, 1, At, B1); PG8_BAR; PG8_SCHED;
.LBB0_1309:
	ds_read_b128 v[128:131], v161
	ds_read_b128 v[132:135], v161 offset:1024
	ds_read_b128 v[148:151], v161 offset:2048
	ds_read_b128 v[152:155], v161 offset:3072
	ds_read_b128 v[166:169], v162
	ds_read_b128 v[170:173], v162 offset:1024
	ds_read_b128 v[174:177], v162 offset:2048
	ds_read_b128 v[178:181], v162 offset:3072
	s_add_u32 s16, s12, 0xfff80080
	s_addc_u32 s17, s13, -1
	s_cmp_eq_u32 s65, 28
	s_cselect_b32 s19, s39, s17
	s_cselect_b32 s18, s59, s16
	s_cselect_b32 s17, s37, s63
	s_cselect_b32 s16, s61, s62
	ds_read_b128 v[182:185], v163
	ds_read_b128 v[186:189], v163 offset:1024
	ds_read_b128 v[190:193], v163 offset:2048
	ds_read_b128 v[194:197], v163 offset:3072
	ds_read_b128 v[198:201], v163 offset:4096
	ds_read_b128 v[202:205], v163 offset:5120
	ds_read_b128 v[206:209], v163 offset:6144
	ds_read_b128 v[210:213], v163 offset:7168
	s_add_u32 s98, s12, 0xfff80000
	s_addc_u32 s99, s13, -1
	s_mov_b32 m0, s33
	s_nop 0
	global_load_lds_dwordx4 v136, s[98:99]
	s_mov_b32 m0, s34
	s_nop 0
	global_load_lds_dwordx4 v140, s[98:99]
	s_add_i32 m0, s5, 0xc000
	s_nop 0
	global_load_lds_dwordx4 v144, s[12:13]
	s_add_i32 m0, s5, 0xe000
	s_nop 0
	global_load_lds_dwordx4 v146, s[12:13]
	s_waitcnt vmcnt(8)
	s_waitcnt lgkmcnt(0)
	s_barrier
	s_setprio 1
	s_waitcnt lgkmcnt(0)
	v_mfma_f32_16x16x32_bf16 v[124:127], v[128:131], v[182:185], v[124:127]
	v_mfma_f32_16x16x32_bf16 v[120:123], v[148:151], v[182:185], v[120:123]
	v_mfma_f32_16x16x32_bf16 v[108:111], v[128:131], v[190:193], v[108:111]
	v_mfma_f32_16x16x32_bf16 v[104:107], v[148:151], v[190:193], v[104:107]
	v_mfma_f32_16x16x32_bf16 v[92:95], v[128:131], v[198:201], v[92:95]
	v_mfma_f32_16x16x32_bf16 v[88:91], v[148:151], v[198:201], v[88:91]
	v_mfma_f32_16x16x32_bf16 v[76:79], v[128:131], v[206:209], v[76:79]
	v_mfma_f32_16x16x32_bf16 v[72:75], v[148:151], v[206:209], v[72:75]
	v_mfma_f32_16x16x32_bf16 v[124:127], v[132:135], v[186:189], v[124:127]
	v_mfma_f32_16x16x32_bf16 v[120:123], v[152:155], v[186:189], v[120:123]
	v_mfma_f32_16x16x32_bf16 v[108:111], v[132:135], v[194:197], v[108:111]
	v_mfma_f32_16x16x32_bf16 v[104:107], v[152:155], v[194:197], v[104:107]
	v_mfma_f32_16x16x32_bf16 v[92:95], v[132:135], v[202:205], v[92:95]
	v_mfma_f32_16x16x32_bf16 v[88:91], v[152:155], v[202:205], v[88:91]
	v_mfma_f32_16x16x32_bf16 v[76:79], v[132:135], v[210:213], v[76:79]
	v_mfma_f32_16x16x32_bf16 v[72:75], v[152:155], v[210:213], v[72:75]
	s_setprio 0
	s_setprio 1
	v_mfma_f32_16x16x32_bf16 v[116:119], v[166:169], v[182:185], v[116:119]
	v_mfma_f32_16x16x32_bf16 v[112:115], v[174:177], v[182:185], v[112:115]
	v_mfma_f32_16x16x32_bf16 v[100:103], v[166:169], v[190:193], v[100:103]
	v_mfma_f32_16x16x32_bf16 v[96:99], v[174:177], v[190:193], v[96:99]
	v_mfma_f32_16x16x32_bf16 v[84:87], v[166:169], v[198:201], v[84:87]
	v_mfma_f32_16x16x32_bf16 v[80:83], v[174:177], v[198:201], v[80:83]
	v_mfma_f32_16x16x32_bf16 v[68:71], v[166:169], v[206:209], v[68:71]
	v_mfma_f32_16x16x32_bf16 v[64:67], v[174:177], v[206:209], v[64:67]
	v_mfma_f32_16x16x32_bf16 v[116:119], v[170:173], v[186:189], v[116:119]
	v_mfma_f32_16x16x32_bf16 v[112:115], v[178:181], v[186:189], v[112:115]
	v_mfma_f32_16x16x32_bf16 v[100:103], v[170:173], v[194:197], v[100:103]
	v_mfma_f32_16x16x32_bf16 v[96:99], v[178:181], v[194:197], v[96:99]
	v_mfma_f32_16x16x32_bf16 v[84:87], v[170:173], v[202:205], v[84:87]
	v_mfma_f32_16x16x32_bf16 v[80:83], v[178:181], v[202:205], v[80:83]
	v_mfma_f32_16x16x32_bf16 v[68:71], v[170:173], v[210:213], v[68:71]
	v_mfma_f32_16x16x32_bf16 v[64:67], v[178:181], v[210:213], v[64:67]
	s_setprio 0
	s_barrier
	s_add_i32 s66, s56, s4
	s_mov_b32 m0, s66
	ds_read_b128 v[182:185], v163 offset:16384
	ds_read_b128 v[186:189], v163 offset:17408
	ds_read_b128 v[190:193], v163 offset:18432
	ds_read_b128 v[194:197], v163 offset:19456
	ds_read_b128 v[198:201], v163 offset:20480
	ds_read_b128 v[202:205], v163 offset:21504
	ds_read_b128 v[206:209], v163 offset:22528
	ds_read_b128 v[210:213], v163 offset:23552
	global_load_lds_dwordx4 v138, s[16:17]
	s_add_i32 m0, s66, 0x2000
	s_add_u32 s66, s16, 0x80000
	s_addc_u32 s67, s17, 0
	s_add_i32 s68, s57, s4
	global_load_lds_dwordx4 v142, s[16:17]
	s_mov_b32 m0, s68
	s_nop 0
	global_load_lds_dwordx4 v138, s[66:67]
	s_add_i32 m0, s68, 0x2000
	s_nop 0
	global_load_lds_dwordx4 v142, s[66:67]
	s_waitcnt vmcnt(6)
	s_waitcnt lgkmcnt(0)
	s_barrier
	s_setprio 1
	s_waitcnt lgkmcnt(0)
	v_mfma_f32_16x16x32_bf16 v[60:63], v[128:131], v[182:185], v[60:63]
	v_mfma_f32_16x16x32_bf16 v[56:59], v[148:151], v[182:185], v[56:59]
	v_mfma_f32_16x16x32_bf16 v[44:47], v[128:131], v[190:193], v[44:47]
	v_mfma_f32_16x16x32_bf16 v[40:43], v[148:151], v[190:193], v[40:43]
	v_mfma_f32_16x16x32_bf16 v[28:31], v[128:131], v[198:201], v[28:31]
	v_mfma_f32_16x16x32_bf16 v[24:27], v[148:151], v[198:201], v[24:27]
	v_mfma_f32_16x16x32_bf16 v[12:15], v[128:131], v[206:209], v[12:15]
	v_mfma_f32_16x16x32_bf16 v[8:11], v[148:151], v[206:209], v[8:11]
	v_mfma_f32_16x16x32_bf16 v[60:63], v[132:135], v[186:189], v[60:63]
	v_mfma_f32_16x16x32_bf16 v[56:59], v[152:155], v[186:189], v[56:59]
	v_mfma_f32_16x16x32_bf16 v[44:47], v[132:135], v[194:197], v[44:47]
	v_mfma_f32_16x16x32_bf16 v[40:43], v[152:155], v[194:197], v[40:43]
	v_mfma_f32_16x16x32_bf16 v[28:31], v[132:135], v[202:205], v[28:31]
	v_mfma_f32_16x16x32_bf16 v[24:27], v[152:155], v[202:205], v[24:27]
	v_mfma_f32_16x16x32_bf16 v[12:15], v[132:135], v[210:213], v[12:15]
	v_mfma_f32_16x16x32_bf16 v[8:11], v[152:155], v[210:213], v[8:11]
	s_setprio 0
	s_setprio 1
	v_mfma_f32_16x16x32_bf16 v[52:55], v[166:169], v[182:185], v[52:55]
	v_mfma_f32_16x16x32_bf16 v[48:51], v[174:177], v[182:185], v[48:51]
	v_mfma_f32_16x16x32_bf16 v[36:39], v[166:169], v[190:193], v[36:39]
	v_mfma_f32_16x16x32_bf16 v[32:35], v[174:177], v[190:193], v[32:35]
	v_mfma_f32_16x16x32_bf16 v[20:23], v[166:169], v[198:201], v[20:23]
	v_mfma_f32_16x16x32_bf16 v[16:19], v[174:177], v[198:201], v[16:19]
	v_mfma_f32_16x16x32_bf16 v[4:7], v[166:169], v[206:209], v[4:7]
	v_mfma_f32_16x16x32_bf16 v[0:3], v[174:177], v[206:209], v[0:3]
	v_mfma_f32_16x16x32_bf16 v[52:55], v[170:173], v[186:189], v[52:55]
	v_mfma_f32_16x16x32_bf16 v[48:51], v[178:181], v[186:189], v[48:51]
	v_mfma_f32_16x16x32_bf16 v[36:39], v[170:173], v[194:197], v[36:39]
	v_mfma_f32_16x16x32_bf16 v[32:35], v[178:181], v[194:197], v[32:35]
	v_mfma_f32_16x16x32_bf16 v[20:23], v[170:173], v[202:205], v[20:23]
	v_mfma_f32_16x16x32_bf16 v[16:19], v[178:181], v[202:205], v[16:19]
	v_mfma_f32_16x16x32_bf16 v[4:7], v[170:173], v[210:213], v[4:7]
	v_mfma_f32_16x16x32_bf16 v[0:3], v[178:181], v[210:213], v[0:3]
	s_setprio 0
	s_barrier
; #define PG8_STAGE(bufoff, gbase, voff) do { _Pragma("unroll") for (int _i = 0; _i < 2; ++_i) \
;         __builtin_amdgcn_global_load_lds((const unsigned*)((const char*)(gbase) + (voff)[_i]), (PG8_LAS unsigned*)(lds + (bufoff) + ldsw + _i * 8192), 16, 0, 0); } while (0)
; #define PG8_LDA(dst, b, h) do { _Pragma("unroll") for (int m = 0; m < 4; ++m) _Pragma("unroll") for (int k = 0; k < 2; ++k) dst[m][k] = *(const PG8_LAS bf16x8*)(lds + PG8_SA(b, h) + aoff + m * 2048 + k * 1024); } while (0)
; #define PG8_LDB(dst, b, h) do { _Pragma("unroll") for (int n = 0; n < 2; ++n) _Pragma("unroll") for (int k = 0; k < 2; ++k) dst[n][k] = *(const PG8_LAS bf16x8*)(lds + PG8_SB(b, h) + boff + n * 2048 + k * 1024); } while (0)
; #define PG8_MMA(ai, bj, At, Bt) do { __builtin_amdgcn_s_setprio(1); _Pragma("unroll") for (int m = 0; m < 4; ++m) _Pragma("unroll") for (int n = 0; n < 2; ++n) _Pragma("unroll") for (int k = 0; k < 2; ++k) \
;         acc[ai][bj][m][n] = __builtin_amdgcn_mfma_f32_16x16x32_bf16(Bt[n][k], At[m][k], acc[ai][bj][m][n], 0, 0, 0); __builtin_amdgcn_s_setprio(0); } while (0)
; #define PG8_WAIT_V(n) asm volatile("s_waitcnt vmcnt(" #n ")" ::: "memory")
; #define PG8_WAIT_L(n) asm volatile("s_waitcnt lgkmcnt(" #n ")" ::: "memory")
; #define PG8_BAR __builtin_amdgcn_s_barrier()
; #define PG8_SCHED __builtin_amdgcn_sched_barrier(0)
; template <class Epi, class Sched, bool ALIGN_EPI = false, bool SP2 = false>
; __device__ __forceinline__ void gemm_phase(PG8_LAS unsigned char* lds, const Gemm g, const Sched& S, const Epi& E) {
;     ...
;             PG8_LDB(B0, 1, 0); PG8_LDB(B1, 1, 1); PG8_SCHED; PG8_LDA(At, 1, 0); PG8_STAGE(PG8_SA(0, 1), a2 + hstepA, voffA);
;             PG8_WAIT_V(8); PG8_WAIT_L(0); PG8_BAR; PG8_MMA(0, 0, At, B0); PG8_MMA(0, 1, At, B1); PG8_BAR; PG8_SCHED;
;             PG8_LDA(At, 1, 1); PG8_STAGE(PG8_SB(1, 0), b3, voffB); PG8_STAGE(PG8_SB(1, 1), b3 + hstepB, voffB); PG8_STAGE(PG8_SA(1, 0), a3, voffA);
;             PG8_WAIT_V(8); PG8_WAIT_L(0); PG8_BAR; PG8_MMA(1, 0, At, B0); PG8_MMA(1, 1, At, B1); PG8_BAR; PG8_SCHED;
	s_add_i32 s66, 0, 0x18000
	s_add_i32 s67, 0, 0x1c000
	v_add_u32_e32 v152, s66, v160
	v_add_u32_e32 v165, s67, v160
	ds_read_b128 v[128:131], v152
	ds_read_b128 v[132:135], v152 offset:1024
	ds_read_b128 v[148:151], v152 offset:2048
	ds_read_b128 v[152:155], v152 offset:3072
	ds_read_b128 v[166:169], v165
	ds_read_b128 v[170:173], v165 offset:1024
	ds_read_b128 v[174:177], v165 offset:2048
	ds_read_b128 v[178:181], v165 offset:3072
	s_mov_b64 s[100:101], s[18:19]
	s_add_u32 s18, s18, 0x80000
	s_addc_u32 s19, s19, 0
	ds_read_b128 v[182:185], v163 offset:32768
	ds_read_b128 v[186:189], v163 offset:33792
	ds_read_b128 v[190:193], v163 offset:34816
	ds_read_b128 v[194:197], v163 offset:35840
	ds_read_b128 v[198:201], v163 offset:36864
	ds_read_b128 v[202:205], v163 offset:37888
	ds_read_b128 v[206:209], v163 offset:38912
	ds_read_b128 v[210:213], v163 offset:39936
	s_mov_b32 m0, s5
	s_nop 0
	global_load_lds_dwordx4 v136, s[100:101]
	s_mov_b32 m0, s6
	s_nop 0
	global_load_lds_dwordx4 v140, s[100:101]
	s_mov_b32 m0, s7
	s_nop 0
	global_load_lds_dwordx4 v136, s[18:19]
	s_mov_b32 m0, s20
	s_nop 0
	global_load_lds_dwordx4 v140, s[18:19]
	s_waitcnt vmcnt(8)
	s_waitcnt lgkmcnt(0)
	s_barrier
	s_setprio 1
	s_waitcnt lgkmcnt(0)
	v_mfma_f32_16x16x32_bf16 v[124:127], v[128:131], v[182:185], v[124:127]
	v_mfma_f32_16x16x32_bf16 v[120:123], v[148:151], v[182:185], v[120:123]
	v_mfma_f32_16x16x32_bf16 v[108:111], v[128:131], v[190:193], v[108:111]
	v_mfma_f32_16x16x32_bf16 v[104:107], v[148:151], v[190:193], v[104:107]
	v_mfma_f32_16x16x32_bf16 v[92:95], v[128:131], v[198:201], v[92:95]
	v_mfma_f32_16x16x32_bf16 v[88:91], v[148:151], v[198:201], v[88:91]
	v_mfma_f32_16x16x32_bf16 v[76:79], v[128:131], v[206:209], v[76:79]
	v_mfma_f32_16x16x32_bf16 v[72:75], v[148:151], v[206:209], v[72:75]
	v_mfma_f32_16x16x32_bf16 v[124:127], v[132:135], v[186:189], v[124:127]
	v_mfma_f32_16x16x32_bf16 v[120:123], v[152:155], v[186:189], v[120:123]
	v_mfma_f32_16x16x32_bf16 v[108:111], v[132:135], v[194:197], v[108:111]
	v_mfma_f32_16x16x32_bf16 v[104:107], v[152:155], v[194:197], v[104:107]
	v_mfma_f32_16x16x32_bf16 v[92:95], v[132:135], v[202:205], v[92:95]
	v_mfma_f32_16x16x32_bf16 v[88:91], v[152:155], v[202:205], v[88:91]
	v_mfma_f32_16x16x32_bf16 v[76:79], v[132:135], v[210:213], v[76:79]
	v_mfma_f32_16x16x32_bf16 v[72:75], v[152:155], v[210:213], v[72:75]
	s_setprio 0
	s_setprio 1
	v_mfma_f32_16x16x32_bf16 v[116:119], v[166:169], v[182:185], v[116:119]
	v_mfma_f32_16x16x32_bf16 v[112:115], v[174:177], v[182:185], v[112:115]
	v_mfma_f32_16x16x32_bf16 v[100:103], v[166:169], v[190:193], v[100:103]
	v_mfma_f32_16x16x32_bf16 v[96:99], v[174:177], v[190:193], v[96:99]
	v_mfma_f32_16x16x32_bf16 v[84:87], v[166:169], v[198:201], v[84:87]
	v_mfma_f32_16x16x32_bf16 v[80:83], v[174:177], v[198:201], v[80:83]
	v_mfma_f32_16x16x32_bf16 v[68:71], v[166:169], v[206:209], v[68:71]
	v_mfma_f32_16x16x32_bf16 v[64:67], v[174:177], v[206:209], v[64:67]
	v_mfma_f32_16x16x32_bf16 v[116:119], v[170:173], v[186:189], v[116:119]
	v_mfma_f32_16x16x32_bf16 v[112:115], v[178:181], v[186:189], v[112:115]
	v_mfma_f32_16x16x32_bf16 v[100:103], v[170:173], v[194:197], v[100:103]
	v_mfma_f32_16x16x32_bf16 v[96:99], v[178:181], v[194:197], v[96:99]
	v_mfma_f32_16x16x32_bf16 v[84:87], v[170:173], v[202:205], v[84:87]
	v_mfma_f32_16x16x32_bf16 v[80:83], v[178:181], v[202:205], v[80:83]
	v_mfma_f32_16x16x32_bf16 v[68:71], v[170:173], v[210:213], v[68:71]
	v_mfma_f32_16x16x32_bf16 v[64:67], v[178:181], v[210:213], v[64:67]
	s_setprio 0
	s_barrier
	s_add_i32 s18, s66, s4
	s_add_u32 s98, s16, 0x80
	s_addc_u32 s99, s17, 0
	s_mov_b32 m0, s18
	ds_read_b128 v[182:185], v163 offset:49152
	ds_read_b128 v[186:189], v163 offset:50176
	ds_read_b128 v[190:193], v163 offset:51200
	ds_read_b128 v[194:197], v163 offset:52224
	ds_read_b128 v[198:201], v163 offset:53248
	ds_read_b128 v[202:205], v163 offset:54272
	ds_read_b128 v[206:209], v163 offset:55296
	ds_read_b128 v[210:213], v163 offset:56320
	global_load_lds_dwordx4 v138, s[98:99]
	s_add_i32 m0, s18, 0x2000
	s_add_u32 s16, s16, 0x80080
	s_addc_u32 s17, s17, 0
	s_add_i32 s18, s67, s4
	global_load_lds_dwordx4 v142, s[98:99]
	s_mov_b32 m0, s18
	s_nop 0
	global_load_lds_dwordx4 v138, s[16:17]
	s_add_i32 m0, s18, 0x2000
	s_nop 0
	global_load_lds_dwordx4 v142, s[16:17]
	s_waitcnt vmcnt(6)
	s_waitcnt lgkmcnt(0)
	s_barrier
	s_setprio 1
	s_waitcnt lgkmcnt(0)
	v_mfma_f32_16x16x32_bf16 v[60:63], v[128:131], v[182:185], v[60:63]
	v_mfma_f32_16x16x32_bf16 v[56:59], v[148:151], v[182:185], v[56:59]
	v_mfma_f32_16x16x32_bf16 v[44:47], v[128:131], v[190:193], v[44:47]
	v_mfma_f32_16x16x32_bf16 v[40:43], v[148:151], v[190:193], v[40:43]
	v_mfma_f32_16x16x32_bf16 v[28:31], v[128:131], v[198:201], v[28:31]
	v_mfma_f32_16x16x32_bf16 v[24:27], v[148:151], v[198:201], v[24:27]
	v_mfma_f32_16x16x32_bf16 v[12:15], v[128:131], v[206:209], v[12:15]
	v_mfma_f32_16x16x32_bf16 v[8:11], v[148:151], v[206:209], v[8:11]
	v_mfma_f32_16x16x32_bf16 v[60:63], v[132:135], v[186:189], v[60:63]
	v_mfma_f32_16x16x32_bf16 v[56:59], v[152:155], v[186:189], v[56:59]
	v_mfma_f32_16x16x32_bf16 v[44:47], v[132:135], v[194:197], v[44:47]
	v_mfma_f32_16x16x32_bf16 v[40:43], v[152:155], v[194:197], v[40:43]
	v_mfma_f32_16x16x32_bf16 v[28:31], v[132:135], v[202:205], v[28:31]
	v_mfma_f32_16x16x32_bf16 v[24:27], v[152:155], v[202:205], v[24:27]
	v_mfma_f32_16x16x32_bf16 v[12:15], v[132:135], v[210:213], v[12:15]
	v_mfma_f32_16x16x32_bf16 v[8:11], v[152:155], v[210:213], v[8:11]
	s_setprio 0
	s_setprio 1
	v_mfma_f32_16x16x32_bf16 v[52:55], v[166:169], v[182:185], v[52:55]
	v_mfma_f32_16x16x32_bf16 v[48:51], v[174:177], v[182:185], v[48:51]
	v_mfma_f32_16x16x32_bf16 v[36:39], v[166:169], v[190:193], v[36:39]
	v_mfma_f32_16x16x32_bf16 v[32:35], v[174:177], v[190:193], v[32:35]
	v_mfma_f32_16x16x32_bf16 v[20:23], v[166:169], v[198:201], v[20:23]
	v_mfma_f32_16x16x32_bf16 v[16:19], v[174:177], v[198:201], v[16:19]
	v_mfma_f32_16x16x32_bf16 v[4:7], v[166:169], v[206:209], v[4:7]
	v_mfma_f32_16x16x32_bf16 v[0:3], v[174:177], v[206:209], v[0:3]
	v_mfma_f32_16x16x32_bf16 v[52:55], v[170:173], v[186:189], v[52:55]
	v_mfma_f32_16x16x32_bf16 v[48:51], v[178:181], v[186:189], v[48:51]
	v_mfma_f32_16x16x32_bf16 v[36:39], v[170:173], v[194:197], v[36:39]
	v_mfma_f32_16x16x32_bf16 v[32:35], v[178:181], v[194:197], v[32:35]
	v_mfma_f32_16x16x32_bf16 v[20:23], v[170:173], v[202:205], v[20:23]
	v_mfma_f32_16x16x32_bf16 v[16:19], v[178:181], v[202:205], v[16:19]
	v_mfma_f32_16x16x32_bf16 v[4:7], v[170:173], v[210:213], v[4:7]
	v_mfma_f32_16x16x32_bf16 v[0:3], v[178:181], v[210:213], v[0:3]
	s_setprio 0
	s_barrier
	s_add_i32 s65, s65, 2
	s_add_u32 s12, s12, 0x100
	s_addc_u32 s13, s13, 0
	s_add_u32 s62, s62, 0x100
	s_addc_u32 s63, s63, 0
	s_cmp_gt_u32 s65, 29
	s_cbranch_scc0 .LBB0_1309
	s_and_b64 vcc, exec, s[26:27]
	s_cbranch_vccz .LBB0_1312
	s_barrier

; #define PG8_STAGE(bufoff, gbase, voff) do { _Pragma("unroll") for (int _i = 0; _i < 2; ++_i) \
;         __builtin_amdgcn_global_load_lds((const unsigned*)((const char*)(gbase) + (voff)[_i]), (PG8_LAS unsigned*)(lds + (bufoff) + ldsw + _i * 8192), 16, 0, 0); } while (0)
; #define PG8_LDA(dst, b, h) do { _Pragma("unroll") for (int m = 0; m < 4; ++m) _Pragma("unroll") for (int k = 0; k < 2; ++k) dst[m][k] = *(const PG8_LAS bf16x8*)(lds + PG8_SA(b, h) + aoff + m * 2048 + k * 1024); } while (0)
; #define PG8_LDB(dst, b, h) do { _Pragma("unroll") for (int n = 0; n < 2; ++n) _Pragma("unroll") for (int k = 0; k < 2; ++k) dst[n][k] = *(const PG8_LAS bf16x8*)(lds + PG8_SB(b, h) + boff + n * 2048 + k * 1024); } while (0)
; #define PG8_MMA(ai, bj, At, Bt) do { __builtin_amdgcn_s_setprio(1); _Pragma("unroll") for (int m = 0; m < 4; ++m) _Pragma("unroll") for (int n = 0; n < 2; ++n) _Pragma("unroll") for (int k = 0; k < 2; ++k) \
;         acc[ai][bj][m][n] = __builtin_amdgcn_mfma_f32_16x16x32_bf16(Bt[n][k], At[m][k], acc[ai][bj][m][n], 0, 0, 0); __builtin_amdgcn_s_setprio(0); } while (0)
; #define PG8_WAIT_V(n) asm volatile("s_waitcnt vmcnt(" #n ")" ::: "memory")
; #define PG8_WAIT_L(n) asm volatile("s_waitcnt lgkmcnt(" #n ")" ::: "memory")
; #define PG8_BAR __builtin_amdgcn_s_barrier()
; template <class Epi, class Sched, bool ALIGN_EPI = false, bool SP2 = false>
; __device__ __forceinline__ void gemm_phase(PG8_LAS unsigned char* lds, const Gemm g, const Sched& S, const Epi& E) {
;     ...
;             const char* a1 = cA + (size_t)(t + 1) * kstep;
;             const char* a2 = last ? nA : cA + (size_t)(t + 2) * kstep; const char* b2 = last ? nB : cB + (size_t)(t + 2) * kstep;
;             const char* a3 = a2 + kstep; const char* b3 = b2 + kstep;
;             if (last && has_next) S.a_ready(nxt);
;             if constexpr (SP2) {
;             PG8_LDB(B0, 0, 0); PG8_LDB(B1, 0, 1); PG8_SCHED; PG8_LDA(At, 0, 0); PG8_STAGE(PG8_SA(1, 1), a1 + hstepA, voffA);
;             PG8_WAIT_V(8); PG8_WAIT_L(0); PG8_BAR; PG8_MMA(0, 0, At, B0); PG8_MMA(0, 1, At, B1); PG8_BAR; PG8_SCHED;
;             PG8_LDA(At, 0, 1); PG8_STAGE(PG8_SB(0, 0), b2, voffB); PG8_STAGE(PG8_SB(0, 1), b2 + hstepB, voffB); PG8_STAGE(PG8_SA(0, 0), a2, voffA);
;             PG8_WAIT_V(8); PG8_WAIT_L(0); PG8_BAR; PG8_MMA(1, 0, At, B0); PG8_MMA(1, 1, At, B1); PG8_BAR; PG8_SCHED;
.LBB0_1738:
	ds_read_b128 v[144:147], v151
	ds_read_b128 v[154:157], v151 offset:1024
	ds_read_b128 v[158:161], v151 offset:2048
	ds_read_b128 v[162:165], v151 offset:3072
	ds_read_b128 v[166:169], v152
	ds_read_b128 v[170:173], v152 offset:1024
	ds_read_b128 v[174:177], v152 offset:2048
	ds_read_b128 v[178:181], v152 offset:3072
	s_add_u32 s34, s20, 0xfffe0080
	s_addc_u32 s35, s21, -1
	s_cmp_eq_u32 s57, 4
	s_cselect_b32 s39, s13, s35
	s_cselect_b32 s38, s27, s34
	s_cselect_b32 s35, s25, s56
	s_cselect_b32 s34, s52, s53
	ds_read_b128 v[182:185], v153
	ds_read_b128 v[186:189], v153 offset:1024
	ds_read_b128 v[190:193], v153 offset:2048
	ds_read_b128 v[194:197], v153 offset:3072
	ds_read_b128 v[198:201], v153 offset:4096
	ds_read_b128 v[202:205], v153 offset:5120
	ds_read_b128 v[206:209], v153 offset:6144
	ds_read_b128 v[210:213], v153 offset:7168
	s_add_u32 s98, s20, 0xfffe0000
	s_addc_u32 s99, s21, -1
	s_mov_b32 m0, s42
	s_nop 0
	global_load_lds_dwordx4 v128, s[98:99]
	s_mov_b32 m0, s43
	s_nop 0
	global_load_lds_dwordx4 v132, s[98:99]
	s_add_i32 m0, s5, 0xc000
	s_nop 0
	global_load_lds_dwordx4 v136, s[20:21]
	s_add_i32 m0, s5, 0xe000
	s_nop 0
	global_load_lds_dwordx4 v138, s[20:21]
	s_waitcnt vmcnt(8)
	s_waitcnt lgkmcnt(0)
	s_barrier
	s_setprio 1
	s_waitcnt lgkmcnt(0)
	v_mfma_f32_16x16x32_bf16 v[124:127], v[144:147], v[182:185], v[124:127]
	v_mfma_f32_16x16x32_bf16 v[120:123], v[158:161], v[182:185], v[120:123]
	v_mfma_f32_16x16x32_bf16 v[108:111], v[144:147], v[190:193], v[108:111]
	v_mfma_f32_16x16x32_bf16 v[104:107], v[158:161], v[190:193], v[104:107]
	v_mfma_f32_16x16x32_bf16 v[92:95], v[144:147], v[198:201], v[92:95]
	v_mfma_f32_16x16x32_bf16 v[88:91], v[158:161], v[198:201], v[88:91]
	v_mfma_f32_16x16x32_bf16 v[76:79], v[144:147], v[206:209], v[76:79]
	v_mfma_f32_16x16x32_bf16 v[72:75], v[158:161], v[206:209], v[72:75]
	v_mfma_f32_16x16x32_bf16 v[124:127], v[154:157], v[186:189], v[124:127]
	v_mfma_f32_16x16x32_bf16 v[120:123], v[162:165], v[186:189], v[120:123]
	v_mfma_f32_16x16x32_bf16 v[108:111], v[154:157], v[194:197], v[108:111]
	v_mfma_f32_16x16x32_bf16 v[104:107], v[162:165], v[194:197], v[104:107]
	v_mfma_f32_16x16x32_bf16 v[92:95], v[154:157], v[202:205], v[92:95]
	v_mfma_f32_16x16x32_bf16 v[88:91], v[162:165], v[202:205], v[88:91]
	v_mfma_f32_16x16x32_bf16 v[76:79], v[154:157], v[210:213], v[76:79]
	v_mfma_f32_16x16x32_bf16 v[72:75], v[162:165], v[210:213], v[72:75]
	s_setprio 0
	s_setprio 1
	v_mfma_f32_16x16x32_bf16 v[116:119], v[166:169], v[182:185], v[116:119]
	v_mfma_f32_16x16x32_bf16 v[112:115], v[174:177], v[182:185], v[112:115]
	v_mfma_f32_16x16x32_bf16 v[100:103], v[166:169], v[190:193], v[100:103]
	v_mfma_f32_16x16x32_bf16 v[96:99], v[174:177], v[190:193], v[96:99]
	v_mfma_f32_16x16x32_bf16 v[84:87], v[166:169], v[198:201], v[84:87]
	v_mfma_f32_16x16x32_bf16 v[80:83], v[174:177], v[198:201], v[80:83]
	v_mfma_f32_16x16x32_bf16 v[68:71], v[166:169], v[206:209], v[68:71]
	v_mfma_f32_16x16x32_bf16 v[64:67], v[174:177], v[206:209], v[64:67]
	v_mfma_f32_16x16x32_bf16 v[116:119], v[170:173], v[186:189], v[116:119]
	v_mfma_f32_16x16x32_bf16 v[112:115], v[178:181], v[186:189], v[112:115]
	v_mfma_f32_16x16x32_bf16 v[100:103], v[170:173], v[194:197], v[100:103]
	v_mfma_f32_16x16x32_bf16 v[96:99], v[178:181], v[194:197], v[96:99]
	v_mfma_f32_16x16x32_bf16 v[84:87], v[170:173], v[202:205], v[84:87]
	v_mfma_f32_16x16x32_bf16 v[80:83], v[178:181], v[202:205], v[80:83]
	v_mfma_f32_16x16x32_bf16 v[68:71], v[170:173], v[210:213], v[68:71]
	v_mfma_f32_16x16x32_bf16 v[64:67], v[178:181], v[210:213], v[64:67]
	s_setprio 0
	s_barrier
	s_add_i32 s58, s47, s4
	s_mov_b32 m0, s58
	ds_read_b128 v[182:185], v153 offset:16384
	ds_read_b128 v[186:189], v153 offset:17408
	ds_read_b128 v[190:193], v153 offset:18432
	ds_read_b128 v[194:197], v153 offset:19456
	ds_read_b128 v[198:201], v153 offset:20480
	ds_read_b128 v[202:205], v153 offset:21504
	ds_read_b128 v[206:209], v153 offset:22528
	ds_read_b128 v[210:213], v153 offset:23552
	global_load_lds_dwordx4 v130, s[34:35]
	s_add_i32 m0, s58, 0x2000
	s_add_u32 s58, s34, 0x20000
	s_addc_u32 s59, s35, 0
	s_add_i32 s60, s50, s4
	global_load_lds_dwordx4 v134, s[34:35]
	s_mov_b32 m0, s60
	s_nop 0
	global_load_lds_dwordx4 v130, s[58:59]
	s_add_i32 m0, s60, 0x2000
	s_nop 0
	global_load_lds_dwordx4 v134, s[58:59]
	s_waitcnt vmcnt(6)
	s_waitcnt lgkmcnt(0)
	s_barrier
	s_setprio 1
	s_waitcnt lgkmcnt(0)
	v_mfma_f32_16x16x32_bf16 v[60:63], v[144:147], v[182:185], v[60:63]
	v_mfma_f32_16x16x32_bf16 v[56:59], v[158:161], v[182:185], v[56:59]
	v_mfma_f32_16x16x32_bf16 v[44:47], v[144:147], v[190:193], v[44:47]
	v_mfma_f32_16x16x32_bf16 v[40:43], v[158:161], v[190:193], v[40:43]
	v_mfma_f32_16x16x32_bf16 v[28:31], v[144:147], v[198:201], v[28:31]
	v_mfma_f32_16x16x32_bf16 v[24:27], v[158:161], v[198:201], v[24:27]
	v_mfma_f32_16x16x32_bf16 v[12:15], v[144:147], v[206:209], v[12:15]
	v_mfma_f32_16x16x32_bf16 v[8:11], v[158:161], v[206:209], v[8:11]
	v_mfma_f32_16x16x32_bf16 v[60:63], v[154:157], v[186:189], v[60:63]
	v_mfma_f32_16x16x32_bf16 v[56:59], v[162:165], v[186:189], v[56:59]
	v_mfma_f32_16x16x32_bf16 v[44:47], v[154:157], v[194:197], v[44:47]
	v_mfma_f32_16x16x32_bf16 v[40:43], v[162:165], v[194:197], v[40:43]
	v_mfma_f32_16x16x32_bf16 v[28:31], v[154:157], v[202:205], v[28:31]
	v_mfma_f32_16x16x32_bf16 v[24:27], v[162:165], v[202:205], v[24:27]
	v_mfma_f32_16x16x32_bf16 v[12:15], v[154:157], v[210:213], v[12:15]
	v_mfma_f32_16x16x32_bf16 v[8:11], v[162:165], v[210:213], v[8:11]
	s_setprio 0
	s_setprio 1
	v_mfma_f32_16x16x32_bf16 v[52:55], v[166:169], v[182:185], v[52:55]
	v_mfma_f32_16x16x32_bf16 v[48:51], v[174:177], v[182:185], v[48:51]
	v_mfma_f32_16x16x32_bf16 v[36:39], v[166:169], v[190:193], v[36:39]
	v_mfma_f32_16x16x32_bf16 v[32:35], v[174:177], v[190:193], v[32:35]
	v_mfma_f32_16x16x32_bf16 v[20:23], v[166:169], v[198:201], v[20:23]
	v_mfma_f32_16x16x32_bf16 v[16:19], v[174:177], v[198:201], v[16:19]
	v_mfma_f32_16x16x32_bf16 v[4:7], v[166:169], v[206:209], v[4:7]
	v_mfma_f32_16x16x32_bf16 v[0:3], v[174:177], v[206:209], v[0:3]
	v_mfma_f32_16x16x32_bf16 v[52:55], v[170:173], v[186:189], v[52:55]
	v_mfma_f32_16x16x32_bf16 v[48:51], v[178:181], v[186:189], v[48:51]
	v_mfma_f32_16x16x32_bf16 v[36:39], v[170:173], v[194:197], v[36:39]
	v_mfma_f32_16x16x32_bf16 v[32:35], v[178:181], v[194:197], v[32:35]
	v_mfma_f32_16x16x32_bf16 v[20:23], v[170:173], v[202:205], v[20:23]
	v_mfma_f32_16x16x32_bf16 v[16:19], v[178:181], v[202:205], v[16:19]
	v_mfma_f32_16x16x32_bf16 v[4:7], v[170:173], v[210:213], v[4:7]
	v_mfma_f32_16x16x32_bf16 v[0:3], v[178:181], v[210:213], v[0:3]
	s_setprio 0
	s_barrier
; #define PG8_STAGE(bufoff, gbase, voff) do { _Pragma("unroll") for (int _i = 0; _i < 2; ++_i) \
;         __builtin_amdgcn_global_load_lds((const unsigned*)((const char*)(gbase) + (voff)[_i]), (PG8_LAS unsigned*)(lds + (bufoff) + ldsw + _i * 8192), 16, 0, 0); } while (0)
; #define PG8_LDA(dst, b, h) do { _Pragma("unroll") for (int m = 0; m < 4; ++m) _Pragma("unroll") for (int k = 0; k < 2; ++k) dst[m][k] = *(const PG8_LAS bf16x8*)(lds + PG8_SA(b, h) + aoff + m * 2048 + k * 1024); } while (0)
; #define PG8_LDB(dst, b, h) do { _Pragma("unroll") for (int n = 0; n < 2; ++n) _Pragma("unroll") for (int k = 0; k < 2; ++k) dst[n][k] = *(const PG8_LAS bf16x8*)(lds + PG8_SB(b, h) + boff + n * 2048 + k * 1024); } while (0)
; #define PG8_MMA(ai, bj, At, Bt) do { __builtin_amdgcn_s_setprio(1); _Pragma("unroll") for (int m = 0; m < 4; ++m) _Pragma("unroll") for (int n = 0; n < 2; ++n) _Pragma("unroll") for (int k = 0; k < 2; ++k) \
;         acc[ai][bj][m][n] = __builtin_amdgcn_mfma_f32_16x16x32_bf16(Bt[n][k], At[m][k], acc[ai][bj][m][n], 0, 0, 0); __builtin_amdgcn_s_setprio(0); } while (0)
; #define PG8_WAIT_V(n) asm volatile("s_waitcnt vmcnt(" #n ")" ::: "memory")
; #define PG8_WAIT_L(n) asm volatile("s_waitcnt lgkmcnt(" #n ")" ::: "memory")
; #define PG8_BAR __builtin_amdgcn_s_barrier()
; #define PG8_SCHED __builtin_amdgcn_sched_barrier(0)
; template <class Epi, class Sched, bool ALIGN_EPI = false, bool SP2 = false>
; __device__ __forceinline__ void gemm_phase(PG8_LAS unsigned char* lds, const Gemm g, const Sched& S, const Epi& E) {
;     ...
;             PG8_LDB(B0, 1, 0); PG8_LDB(B1, 1, 1); PG8_SCHED; PG8_LDA(At, 1, 0); PG8_STAGE(PG8_SA(0, 1), a2 + hstepA, voffA);
;             PG8_WAIT_V(8); PG8_WAIT_L(0); PG8_BAR; PG8_MMA(0, 0, At, B0); PG8_MMA(0, 1, At, B1); PG8_BAR; PG8_SCHED;
;             PG8_LDA(At, 1, 1); PG8_STAGE(PG8_SB(1, 0), b3, voffB); PG8_STAGE(PG8_SB(1, 1), b3 + hstepB, voffB); PG8_STAGE(PG8_SA(1, 0), a3, voffA);
;             PG8_WAIT_V(8); PG8_WAIT_L(0); PG8_BAR; PG8_MMA(1, 0, At, B0); PG8_MMA(1, 1, At, B1); PG8_BAR; PG8_SCHED;
	s_add_i32 s58, 0, 0x18000
	s_add_i32 s59, 0, 0x1c000
	v_add_u32_e32 v162, s58, v150
	v_add_u32_e32 v178, s59, v150
	ds_read_b128 v[144:147], v162
	ds_read_b128 v[154:157], v162 offset:1024
	ds_read_b128 v[158:161], v162 offset:2048
	ds_read_b128 v[162:165], v162 offset:3072
	ds_read_b128 v[166:169], v178
	ds_read_b128 v[170:173], v178 offset:1024
	ds_read_b128 v[174:177], v178 offset:2048
	ds_read_b128 v[178:181], v178 offset:3072
	s_mov_b64 s[100:101], s[38:39]
	s_add_u32 s38, s38, 0x20000
	s_addc_u32 s39, s39, 0
	ds_read_b128 v[182:185], v153 offset:32768
	ds_read_b128 v[186:189], v153 offset:33792
	ds_read_b128 v[190:193], v153 offset:34816
	ds_read_b128 v[194:197], v153 offset:35840
	ds_read_b128 v[198:201], v153 offset:36864
	ds_read_b128 v[202:205], v153 offset:37888
	ds_read_b128 v[206:209], v153 offset:38912
	ds_read_b128 v[210:213], v153 offset:39936
	s_mov_b32 m0, s5
	s_nop 0
	global_load_lds_dwordx4 v128, s[100:101]
	s_mov_b32 m0, s6
	s_nop 0
	global_load_lds_dwordx4 v132, s[100:101]
	s_mov_b32 m0, s7
	s_nop 0
	global_load_lds_dwordx4 v128, s[38:39]
	s_mov_b32 m0, s33
	s_nop 0
	global_load_lds_dwordx4 v132, s[38:39]
	s_waitcnt vmcnt(8)
	s_waitcnt lgkmcnt(0)
	s_barrier
	s_setprio 1
	s_waitcnt lgkmcnt(0)
	v_mfma_f32_16x16x32_bf16 v[124:127], v[144:147], v[182:185], v[124:127]
	v_mfma_f32_16x16x32_bf16 v[120:123], v[158:161], v[182:185], v[120:123]
	v_mfma_f32_16x16x32_bf16 v[108:111], v[144:147], v[190:193], v[108:111]
	v_mfma_f32_16x16x32_bf16 v[104:107], v[158:161], v[190:193], v[104:107]
	v_mfma_f32_16x16x32_bf16 v[92:95], v[144:147], v[198:201], v[92:95]
	v_mfma_f32_16x16x32_bf16 v[88:91], v[158:161], v[198:201], v[88:91]
	v_mfma_f32_16x16x32_bf16 v[76:79], v[144:147], v[206:209], v[76:79]
	v_mfma_f32_16x16x32_bf16 v[72:75], v[158:161], v[206:209], v[72:75]
	v_mfma_f32_16x16x32_bf16 v[124:127], v[154:157], v[186:189], v[124:127]
	v_mfma_f32_16x16x32_bf16 v[120:123], v[162:165], v[186:189], v[120:123]
	v_mfma_f32_16x16x32_bf16 v[108:111], v[154:157], v[194:197], v[108:111]
	v_mfma_f32_16x16x32_bf16 v[104:107], v[162:165], v[194:197], v[104:107]
	v_mfma_f32_16x16x32_bf16 v[92:95], v[154:157], v[202:205], v[92:95]
	v_mfma_f32_16x16x32_bf16 v[88:91], v[162:165], v[202:205], v[88:91]
	v_mfma_f32_16x16x32_bf16 v[76:79], v[154:157], v[210:213], v[76:79]
	v_mfma_f32_16x16x32_bf16 v[72:75], v[162:165], v[210:213], v[72:75]
	s_setprio 0
	s_setprio 1
	v_mfma_f32_16x16x32_bf16 v[116:119], v[166:169], v[182:185], v[116:119]
	v_mfma_f32_16x16x32_bf16 v[112:115], v[174:177], v[182:185], v[112:115]
	v_mfma_f32_16x16x32_bf16 v[100:103], v[166:169], v[190:193], v[100:103]
	v_mfma_f32_16x16x32_bf16 v[96:99], v[174:177], v[190:193], v[96:99]
	v_mfma_f32_16x16x32_bf16 v[84:87], v[166:169], v[198:201], v[84:87]
	v_mfma_f32_16x16x32_bf16 v[80:83], v[174:177], v[198:201], v[80:83]
	v_mfma_f32_16x16x32_bf16 v[68:71], v[166:169], v[206:209], v[68:71]
	v_mfma_f32_16x16x32_bf16 v[64:67], v[174:177], v[206:209], v[64:67]
	v_mfma_f32_16x16x32_bf16 v[116:119], v[170:173], v[186:189], v[116:119]
	v_mfma_f32_16x16x32_bf16 v[112:115], v[178:181], v[186:189], v[112:115]
	v_mfma_f32_16x16x32_bf16 v[100:103], v[170:173], v[194:197], v[100:103]
	v_mfma_f32_16x16x32_bf16 v[96:99], v[178:181], v[194:197], v[96:99]
	v_mfma_f32_16x16x32_bf16 v[84:87], v[170:173], v[202:205], v[84:87]
	v_mfma_f32_16x16x32_bf16 v[80:83], v[178:181], v[202:205], v[80:83]
	v_mfma_f32_16x16x32_bf16 v[68:71], v[170:173], v[210:213], v[68:71]
	v_mfma_f32_16x16x32_bf16 v[64:67], v[178:181], v[210:213], v[64:67]
	s_setprio 0
	s_barrier
	s_add_i32 s38, s58, s4
	s_add_u32 s98, s34, 0x80
	s_addc_u32 s99, s35, 0
	s_mov_b32 m0, s38
	ds_read_b128 v[182:185], v153 offset:49152
	ds_read_b128 v[186:189], v153 offset:50176
	ds_read_b128 v[190:193], v153 offset:51200
	ds_read_b128 v[194:197], v153 offset:52224
	ds_read_b128 v[198:201], v153 offset:53248
	ds_read_b128 v[202:205], v153 offset:54272
	ds_read_b128 v[206:209], v153 offset:55296
	ds_read_b128 v[210:213], v153 offset:56320
	global_load_lds_dwordx4 v130, s[98:99]
	s_add_i32 m0, s38, 0x2000
	s_add_u32 s34, s34, 0x20080
	s_addc_u32 s35, s35, 0
	s_add_i32 s38, s59, s4
	global_load_lds_dwordx4 v134, s[98:99]
	s_mov_b32 m0, s38
	s_nop 0
	global_load_lds_dwordx4 v130, s[34:35]
	s_add_i32 m0, s38, 0x2000
	s_nop 0
	global_load_lds_dwordx4 v134, s[34:35]
	s_waitcnt vmcnt(6)
	s_waitcnt lgkmcnt(0)
	s_barrier
	s_setprio 1
	s_waitcnt lgkmcnt(0)
	v_mfma_f32_16x16x32_bf16 v[60:63], v[144:147], v[182:185], v[60:63]
	v_mfma_f32_16x16x32_bf16 v[56:59], v[158:161], v[182:185], v[56:59]
	v_mfma_f32_16x16x32_bf16 v[44:47], v[144:147], v[190:193], v[44:47]
	v_mfma_f32_16x16x32_bf16 v[40:43], v[158:161], v[190:193], v[40:43]
	v_mfma_f32_16x16x32_bf16 v[28:31], v[144:147], v[198:201], v[28:31]
	v_mfma_f32_16x16x32_bf16 v[24:27], v[158:161], v[198:201], v[24:27]
	v_mfma_f32_16x16x32_bf16 v[12:15], v[144:147], v[206:209], v[12:15]
	v_mfma_f32_16x16x32_bf16 v[8:11], v[158:161], v[206:209], v[8:11]
	v_mfma_f32_16x16x32_bf16 v[60:63], v[154:157], v[186:189], v[60:63]
	v_mfma_f32_16x16x32_bf16 v[56:59], v[162:165], v[186:189], v[56:59]
	v_mfma_f32_16x16x32_bf16 v[44:47], v[154:157], v[194:197], v[44:47]
	v_mfma_f32_16x16x32_bf16 v[40:43], v[162:165], v[194:197], v[40:43]
	v_mfma_f32_16x16x32_bf16 v[28:31], v[154:157], v[202:205], v[28:31]
	v_mfma_f32_16x16x32_bf16 v[24:27], v[162:165], v[202:205], v[24:27]
	v_mfma_f32_16x16x32_bf16 v[12:15], v[154:157], v[210:213], v[12:15]
	v_mfma_f32_16x16x32_bf16 v[8:11], v[162:165], v[210:213], v[8:11]
	s_setprio 0
	s_setprio 1
	v_mfma_f32_16x16x32_bf16 v[52:55], v[166:169], v[182:185], v[52:55]
	v_mfma_f32_16x16x32_bf16 v[48:51], v[174:177], v[182:185], v[48:51]
	v_mfma_f32_16x16x32_bf16 v[36:39], v[166:169], v[190:193], v[36:39]
	v_mfma_f32_16x16x32_bf16 v[32:35], v[174:177], v[190:193], v[32:35]
	v_mfma_f32_16x16x32_bf16 v[20:23], v[166:169], v[198:201], v[20:23]
	v_mfma_f32_16x16x32_bf16 v[16:19], v[174:177], v[198:201], v[16:19]
	v_mfma_f32_16x16x32_bf16 v[4:7], v[166:169], v[206:209], v[4:7]
	v_mfma_f32_16x16x32_bf16 v[0:3], v[174:177], v[206:209], v[0:3]
	v_mfma_f32_16x16x32_bf16 v[52:55], v[170:173], v[186:189], v[52:55]
	v_mfma_f32_16x16x32_bf16 v[48:51], v[178:181], v[186:189], v[48:51]
	v_mfma_f32_16x16x32_bf16 v[36:39], v[170:173], v[194:197], v[36:39]
	v_mfma_f32_16x16x32_bf16 v[32:35], v[178:181], v[194:197], v[32:35]
	v_mfma_f32_16x16x32_bf16 v[20:23], v[170:173], v[202:205], v[20:23]
	v_mfma_f32_16x16x32_bf16 v[16:19], v[178:181], v[202:205], v[16:19]
	v_mfma_f32_16x16x32_bf16 v[4:7], v[170:173], v[210:213], v[4:7]
	v_mfma_f32_16x16x32_bf16 v[0:3], v[178:181], v[210:213], v[0:3]
	s_setprio 0
	s_barrier
	s_add_i32 s57, s57, 2
	s_add_u32 s20, s20, 0x100
	s_addc_u32 s21, s21, 0
	s_add_u32 s53, s53, 0x100
	s_addc_u32 s56, s56, 0
	s_cmp_gt_u32 s57, 5
	s_cbranch_scc0 .LBB0_1738
	s_and_b64 vcc, exec, s[22:23]
	s_cbranch_vccz .LBB0_1741
	s_barrier
